# attention main loop unrolled x4 with static LDS ring-stage offsets (no per-tile VALU/SALU address arithmetic in the MFMA half), on top of trimmed GEMM loops
# speedup vs baseline: 1.0087x; 1.0087x over previous
; #define SLOAD(i, k0) do { sr_[i].vs = *(const u32x4*)(vsrc + (k0)); \
;     { const unsigned char* kt_ = Kh + (size_t)(k0) * 192; sr_[i].ks0 = *(const u32x4*)(kt_ + tid * 16); if (k2) sr_[i].ks1 = *(const u32x4*)(kt_ + 8192 + tid * 16); } } while (0)
; __device__ __forceinline__ void attn_body(const unsigned char* __restrict__ Qb, const unsigned char* __restrict__ Kh, const unsigned char* __restrict__ Vt,
;                                           bf16_t* __restrict__ Ob, int seq, char* lds) {
;     ...
;   float m_reg = -1e30f, l_reg = 0; f32x16 o[4] = {}; i32x8 qr[3];
;   const unsigned char* Qw = Qb + (long)(wid * QBLK + r32) * 192 + hi * 32;
; #pragma unroll
;   for (int m = 0; m < 3; ++m) { const u32x4 a0 = *reinterpret_cast<const u32x4*>(Qw + m * 64), a1 = *reinterpret_cast<const u32x4*>(Qw + m * 64 + 16);
;     qr[m] = (i32x8){(int)a0.x, (int)a0.y, (int)a0.z, (int)a0.w, (int)a1.x, (int)a1.y, (int)a1.z, (int)a1.w}; }
;   const unsigned char* vsrc = Vt + (size_t)(tid >> 2) * S_ + (tid & 3) * 16;
;   const int vw = (tid >> 2) * 80 + ((tid & 3) >> 1) * 16 + (tid & 1) * 8;
;   const int kw0 = KSWZ(tid / 12, (tid % 12) * 16), kw1 = KSWZ((tid + 512) / 12, ((tid + 512) % 12) * 16);
;   const bool k2 = tid < 256;
;   struct { u32x4 vs, ks0, ks1; } sr_[SDEPTH];
;     ...
;   f32x16 pA0, pA1, pB0, pB1; float mnA, mnB, alA, alB; i32x8 pa; const int NT = seq / KVBLK;
;     ...
;   int sP = 0, sC = 1, sN = 2;
;   SLOAD(0, 0); asm volatile("s_waitcnt vmcnt(0)" ::: "memory"); SWRITE(0, 0); SLOAD(0, KVBLK); __syncthreads();
;   asm volatile("s_waitcnt vmcnt(0)" ::: "memory"); SWRITE(1, 0); if (2 < NT) SLOAD(0, 2 * KVBLK);
.Latt_p1b:
	s_add_u32 s8, s8, 0x3000
	s_addc_u32 s9, s9, 0
	s_add_u32 s10, s10, 64
	s_addc_u32 s11, s11, 0
	v_mul_u32_u24_e32 v217, 0x50, v225
	v_lshrrev_b32_e32 v230, 1, v228
	v_lshl_add_u32 v217, v230, 4, v217
	v_and_b32_e32 v230, 1, v192
	v_lshl_add_u32 v217, v230, 3, v217
	s_mov_b32 s0, 0x2aaaaaab
	v_mul_hi_u32 v230, v192, s0
	v_lshrrev_b32_e32 v230, 1, v230
	v_add_lshl_u32 v218, v230, v192, 4
	v_add_u32_e32 v226, 0x200, v192
	v_mul_hi_u32 v230, v226, s0
	v_lshrrev_b32_e32 v230, 1, v230
	v_add_lshl_u32 v219, v230, v226, 4
	v_mul_u32_u24_e32 v220, 0xd0, v201
	v_lshl_add_u32 v220, v229, 5, v220
	v_add_u32_e32 v220, 40960, v220
	v_add_u32_e32 v218, 40960, v218
	v_add_u32_e32 v219, 40960, v219
	v_mul_u32_u24_e32 v221, 0x50, v201
	v_lshl_add_u32 v221, v229, 5, v221
	v_lshlrev_b32_e32 v222, 8, v231
	v_add_u32_e32 v222, 0x17000, v222
	v_lshl_add_u32 v223, v229, 4, v222
	v_lshl_add_u32 v222, v201, 2, v222
	v_mov_b64_e32 v[0:1], 0
	v_mov_b64_e32 v[2:3], 0
	v_mov_b64_e32 v[4:5], 0
	v_mov_b64_e32 v[6:7], 0
	v_mov_b64_e32 v[8:9], 0
	v_mov_b64_e32 v[10:11], 0
	v_mov_b64_e32 v[12:13], 0
	v_mov_b64_e32 v[14:15], 0
	v_mov_b64_e32 v[16:17], 0
	v_mov_b64_e32 v[18:19], 0
	v_mov_b64_e32 v[20:21], 0
	v_mov_b64_e32 v[22:23], 0
	v_mov_b64_e32 v[24:25], 0
	v_mov_b64_e32 v[26:27], 0
	v_mov_b64_e32 v[28:29], 0
	v_mov_b64_e32 v[30:31], 0
	v_mov_b64_e32 v[32:33], 0
	v_mov_b64_e32 v[34:35], 0
	v_mov_b64_e32 v[36:37], 0
	v_mov_b64_e32 v[38:39], 0
	v_mov_b64_e32 v[40:41], 0
	v_mov_b64_e32 v[42:43], 0
	v_mov_b64_e32 v[44:45], 0
	v_mov_b64_e32 v[46:47], 0
	v_mov_b64_e32 v[48:49], 0
	v_mov_b64_e32 v[50:51], 0
	v_mov_b64_e32 v[52:53], 0
	v_mov_b64_e32 v[54:55], 0
	v_mov_b64_e32 v[56:57], 0
	v_mov_b64_e32 v[58:59], 0
	v_mov_b64_e32 v[60:61], 0
	v_mov_b64_e32 v[62:63], 0
	v_mov_b32_e32 v193, 0xf149f2ca
	v_mov_b32_e32 v194, 0
	s_mov_b32 s13, 0x40fc551e
	v_mov_b64_e32 v[160:161], 0
	v_mov_b64_e32 v[162:163], 0
	v_mov_b64_e32 v[164:165], 0
	v_mov_b64_e32 v[166:167], 0
	v_mov_b64_e32 v[168:169], 0
	v_mov_b64_e32 v[170:171], 0
	v_mov_b64_e32 v[172:173], 0
	v_mov_b64_e32 v[174:175], 0
	v_mov_b32_e32 v227, 0
	v_mov_b32_e32 v201, 0x7c7c7c7c
	s_waitcnt vmcnt(0)
	ds_write2_b32 v217, v202, v204 offset1:1
	ds_write2_b32 v217, v203, v205 offset0:8 offset1:9
	ds_write_b128 v218, v[206:209] offset:0
	s_cmp_lt_u32 s12, 4
	s_cbranch_scc0 .Latt_p2
	ds_write_b128 v219, v[210:213] offset:0
.Latt_p2:
	v_add_u32_e32 v224, 10240, v217
	v_add_u32_e32 v225, 20480, v217
	ds_write2_b32 v224, v128, v130 offset1:1
	ds_write2_b32 v224, v129, v131 offset0:8 offset1:9
	ds_write_b128 v218, v[132:135] offset:13312
	s_cmp_lt_u32 s12, 4
	s_cbranch_scc0 .Latt_p3
	ds_write_b128 v219, v[136:139] offset:13312

; __device__ __forceinline__ int ltid() { int t = threadIdx.x; asm volatile("" : "+v"(t)); return t; }
; __device__ __forceinline__ void qkt(f32x16& p0, f32x16& p1, const unsigned char* Ks, const i32x8* qr, int r32, int hi) {
;   p0 = f32x16{}; p1 = f32x16{};
; #pragma unroll
;   for (int m = 0; m < 3; ++m) { const int cb = m * 64 + hi * 32;
;     const u32x4 a0 = *reinterpret_cast<const u32x4*>(Ks + KSWZ(r32, cb)), a1 = *reinterpret_cast<const u32x4*>(Ks + KSWZ(r32, cb) + 16);
;     const u32x4 c0 = *reinterpret_cast<const u32x4*>(Ks + KSWZ(32 + r32, cb)), c1 = *reinterpret_cast<const u32x4*>(Ks + KSWZ(32 + r32, cb) + 16);
;     const i32x8 b0 = {(int)a0.x, (int)a0.y, (int)a0.z, (int)a0.w, (int)a1.x, (int)a1.y, (int)a1.z, (int)a1.w};
;     const i32x8 b1 = {(int)c0.x, (int)c0.y, (int)c0.z, (int)c0.w, (int)c1.x, (int)c1.y, (int)c1.z, (int)c1.w};
;     p0 = __builtin_amdgcn_mfma_scale_f32_32x32x64_f8f6f4(b0, qr[m], p0, 0, 0, 0, 0x7F7F7F7F, 0, 0x7F7F7F7F);
;     p1 = __builtin_amdgcn_mfma_scale_f32_32x32x64_f8f6f4(b1, qr[m], p1, 0, 0, 0, 0x7F7F7F7F, 0, 0x7F7F7F7F); }
; }
; __device__ __forceinline__ void pv_d0(f32x16* o, const unsigned char* Vs, const i32x8& pa, int r32, int hi) {
; #pragma unroll
;   for (int d0 = 0; d0 < 4; ++d0) { const unsigned char* vp = Vs + (32 * d0 + r32) * 80 + hi * 32;
;     const u32x4 a0 = *reinterpret_cast<const u32x4*>(vp), a1 = *reinterpret_cast<const u32x4*>(vp + 16);
;     const i32x8 vb = {(int)a0.x, (int)a0.y, (int)a0.z, (int)a0.w, (int)a1.x, (int)a1.y, (int)a1.z, (int)a1.w};
;     o[d0] = __builtin_amdgcn_mfma_scale_f32_32x32x64_f8f6f4(pa, vb, o[d0], 0, 0, 0, 0x7A7A7A7A, 0, 0x7F7F7F7F); }
; }
; __device__ __forceinline__ void attn_body(const unsigned char* __restrict__ Qb, const unsigned char* __restrict__ Kh, const unsigned char* __restrict__ Vt,
;                                           bf16_t* __restrict__ Ob, int seq, char* lds) {
;   const int tid = ltid(), wid = tid >> 6, lane = tid & 63, r32 = lane & 31, hi = lane >> 5;
;   unsigned char* V_lds = (unsigned char*)lds; unsigned char* K_lds = (unsigned char*)(lds + 3 * SHM_V);
;   float* ws = (float*)(lds + 3 * SHM_V + 3 * SHM_K) + wid * 64; float* li_l = ws; float* al_l = ws + 32;
;   float m_reg = -1e30f, l_reg = 0; f32x16 o[4] = {}; i32x8 qr[3];
;   const unsigned char* Qw = Qb + (long)(wid * QBLK + r32) * 192 + hi * 32;
; #pragma unroll
.Latt_p5:
	v_mov_b32_e32 v202, v140
	v_mov_b32_e32 v203, v141
	v_mov_b32_e32 v204, v142
	v_mov_b32_e32 v205, v143
	v_mov_b32_e32 v206, v144
	v_mov_b32_e32 v207, v145
	v_mov_b32_e32 v208, v146
	v_mov_b32_e32 v209, v147
	v_mov_b32_e32 v210, v148
	v_mov_b32_e32 v211, v149
	v_mov_b32_e32 v212, v150
	v_mov_b32_e32 v213, v151
	s_waitcnt lgkmcnt(0)
	s_barrier
	ds_read_b128 v[128:131], v220 offset:0
	ds_read_b128 v[132:135], v220 offset:16
	ds_read_b128 v[136:139], v220 offset:6656
	ds_read_b128 v[140:143], v220 offset:6672
	ds_read_b128 v[144:147], v220 offset:64
	ds_read_b128 v[148:151], v220 offset:80
	ds_read_b128 v[152:155], v220 offset:6720
	ds_read_b128 v[156:159], v220 offset:6736
	s_mov_b32 s6, 0
.Latt_loop:
	s_cmp_eq_u32 s6, 0
	s_cbranch_scc1 .Latt_m_first
	s_add_u32 s4, s6, 2
	ds_read_b128 v[176:179], v221 offset:30720
	ds_read_b128 v[180:183], v221 offset:30736
	ds_read_b128 v[184:187], v221 offset:33280
	ds_read_b128 v[188:191], v221 offset:33296
	s_waitcnt lgkmcnt(4)
	v_mfma_scale_f32_32x32x64_f8f6f4 v[64:79], v[128:135], v[96:103], v[160:175], v235, v201 op_sel_hi:[0,0,0]
	ds_read_b128 v[128:131], v220 offset:128
	ds_read_b128 v[132:135], v220 offset:144
	v_mfma_scale_f32_32x32x64_f8f6f4 v[80:95], v[136:143], v[96:103], v[160:175], v235, v201 op_sel_hi:[0,0,0]
	ds_read_b128 v[136:139], v220 offset:6784
	ds_read_b128 v[140:143], v220 offset:6800
	s_cmp_lt_u32 s4, 128
	s_cbranch_scc0 .Latt_ms0_nowr
	s_waitcnt vmcnt(0)
	ds_write2_b32 v225, v202, v204 offset1:1
	ds_write2_b32 v225, v203, v205 offset0:8 offset1:9
	ds_write_b128 v218, v[206:209] offset:26624
	s_cmp_lt_u32 s12, 4
	s_cbranch_scc0 .Latt_ms0_w1
	ds_write_b128 v219, v[210:213] offset:26624
.Latt_ms0_w1:
.Latt_ms0_nowr:
	v_mfma_scale_f32_32x32x64_f8f6f4 v[64:79], v[144:151], v[104:111], v[64:79], v235, v201 op_sel_hi:[0,0,0]
	ds_read_b128 v[144:147], v220 offset:13376
	ds_read_b128 v[148:151], v220 offset:13392
	v_mfma_scale_f32_32x32x64_f8f6f4 v[80:95], v[152:159], v[104:111], v[80:95], v235, v201 op_sel_hi:[0,0,0]
	ds_read_b128 v[152:155], v220 offset:20032
	ds_read_b128 v[156:159], v220 offset:20048
	s_cmp_lt_u32 s4, 127
	s_cbranch_scc0 .Latt_ms0_nold
	global_load_dwordx4 v[202:205], v216, s[10:11]
	global_load_dwordx4 v[206:209], v214, s[8:9]
	s_cmp_lt_u32 s12, 4
	s_cbranch_scc0 .Latt_ms0_l1
	global_load_dwordx4 v[210:213], v215, s[8:9]

; __device__ __forceinline__ void qkt(f32x16& p0, f32x16& p1, const unsigned char* Ks, const i32x8* qr, int r32, int hi) {
;   p0 = f32x16{}; p1 = f32x16{};
; #pragma unroll
;   for (int m = 0; m < 3; ++m) { const int cb = m * 64 + hi * 32;
;     const u32x4 a0 = *reinterpret_cast<const u32x4*>(Ks + KSWZ(r32, cb)), a1 = *reinterpret_cast<const u32x4*>(Ks + KSWZ(r32, cb) + 16);
;     const u32x4 c0 = *reinterpret_cast<const u32x4*>(Ks + KSWZ(32 + r32, cb)), c1 = *reinterpret_cast<const u32x4*>(Ks + KSWZ(32 + r32, cb) + 16);
;     const i32x8 b0 = {(int)a0.x, (int)a0.y, (int)a0.z, (int)a0.w, (int)a1.x, (int)a1.y, (int)a1.z, (int)a1.w};
;     const i32x8 b1 = {(int)c0.x, (int)c0.y, (int)c0.z, (int)c0.w, (int)c1.x, (int)c1.y, (int)c1.z, (int)c1.w};
;     p0 = __builtin_amdgcn_mfma_scale_f32_32x32x64_f8f6f4(b0, qr[m], p0, 0, 0, 0, 0x7F7F7F7F, 0, 0x7F7F7F7F);
;     p1 = __builtin_amdgcn_mfma_scale_f32_32x32x64_f8f6f4(b1, qr[m], p1, 0, 0, 0, 0x7F7F7F7F, 0, 0x7F7F7F7F); }
; }
; __device__ __forceinline__ void pv_d0(f32x16* o, const unsigned char* Vs, const i32x8& pa, int r32, int hi) {
; #pragma unroll
;   for (int d0 = 0; d0 < 4; ++d0) { const unsigned char* vp = Vs + (32 * d0 + r32) * 80 + hi * 32;
;     const u32x4 a0 = *reinterpret_cast<const u32x4*>(vp), a1 = *reinterpret_cast<const u32x4*>(vp + 16);
;     const i32x8 vb = {(int)a0.x, (int)a0.y, (int)a0.z, (int)a0.w, (int)a1.x, (int)a1.y, (int)a1.z, (int)a1.w};
;     o[d0] = __builtin_amdgcn_mfma_scale_f32_32x32x64_f8f6f4(pa, vb, o[d0], 0, 0, 0, 0x7A7A7A7A, 0, 0x7F7F7F7F); }
; }
.Latt_ms0_nold:
	s_waitcnt lgkmcnt(9)
	v_mfma_scale_f32_32x32x64_f8f6f4 v[64:79], v[128:135], v[112:119], v[64:79], v235, v201 op_sel_hi:[0,0,0]
	ds_read_b128 v[128:131], v220 offset:13312
	ds_read_b128 v[132:135], v220 offset:13328
	s_waitcnt lgkmcnt(9)
	v_mfma_scale_f32_32x32x64_f8f6f4 v[80:95], v[136:143], v[112:119], v[80:95], v235, v201 op_sel_hi:[0,0,0]
	ds_read_b128 v[136:139], v220 offset:19968
	ds_read_b128 v[140:143], v220 offset:19984
	s_waitcnt lgkmcnt(8)
	v_mfma_scale_f32_32x32x64_f8f6f4 v[0:15], v[120:127], v[176:183], v[0:15], v237, v235 op_sel_hi:[0,0,0]
	ds_read_b128 v[176:179], v221 offset:35840
	ds_read_b128 v[180:183], v221 offset:35856
	v_mfma_scale_f32_32x32x64_f8f6f4 v[16:31], v[120:127], v[184:191], v[16:31], v237, v235 op_sel_hi:[0,0,0]
	ds_read_b128 v[184:187], v221 offset:38400
	ds_read_b128 v[188:191], v221 offset:38416
	s_waitcnt lgkmcnt(2)
	v_mfma_scale_f32_32x32x64_f8f6f4 v[32:47], v[120:127], v[176:183], v[32:47], v237, v235 op_sel_hi:[0,0,0]
	s_waitcnt lgkmcnt(0)
	v_mfma_scale_f32_32x32x64_f8f6f4 v[48:63], v[120:127], v[184:191], v[48:63], v237, v235 op_sel_hi:[0,0,0]
	s_branch .Latt_m_done_0
.Latt_m_first:
	s_add_u32 s4, s6, 2
	s_waitcnt lgkmcnt(0)
	v_mfma_scale_f32_32x32x64_f8f6f4 v[64:79], v[128:135], v[96:103], v[160:175], v235, v201 op_sel_hi:[0,0,0]
	ds_read_b128 v[128:131], v220 offset:128
	ds_read_b128 v[132:135], v220 offset:144
	v_mfma_scale_f32_32x32x64_f8f6f4 v[80:95], v[136:143], v[96:103], v[160:175], v235, v201 op_sel_hi:[0,0,0]
	ds_read_b128 v[136:139], v220 offset:6784
	ds_read_b128 v[140:143], v220 offset:6800
	s_cmp_lt_u32 s4, 128
	s_cbranch_scc0 .Latt_mf_nowr
	s_waitcnt vmcnt(0)
	ds_write2_b32 v225, v202, v204 offset1:1
	ds_write2_b32 v225, v203, v205 offset0:8 offset1:9
	ds_write_b128 v218, v[206:209] offset:26624
	s_cmp_lt_u32 s12, 4
	s_cbranch_scc0 .Latt_mf_w1
	ds_write_b128 v219, v[210:213] offset:26624

; __device__ __forceinline__ void qkt(f32x16& p0, f32x16& p1, const unsigned char* Ks, const i32x8* qr, int r32, int hi) {
;   p0 = f32x16{}; p1 = f32x16{};
; #pragma unroll
;   for (int m = 0; m < 3; ++m) { const int cb = m * 64 + hi * 32;
;     const u32x4 a0 = *reinterpret_cast<const u32x4*>(Ks + KSWZ(r32, cb)), a1 = *reinterpret_cast<const u32x4*>(Ks + KSWZ(r32, cb) + 16);
;     const u32x4 c0 = *reinterpret_cast<const u32x4*>(Ks + KSWZ(32 + r32, cb)), c1 = *reinterpret_cast<const u32x4*>(Ks + KSWZ(32 + r32, cb) + 16);
;     const i32x8 b0 = {(int)a0.x, (int)a0.y, (int)a0.z, (int)a0.w, (int)a1.x, (int)a1.y, (int)a1.z, (int)a1.w};
;     const i32x8 b1 = {(int)c0.x, (int)c0.y, (int)c0.z, (int)c0.w, (int)c1.x, (int)c1.y, (int)c1.z, (int)c1.w};
;     p0 = __builtin_amdgcn_mfma_scale_f32_32x32x64_f8f6f4(b0, qr[m], p0, 0, 0, 0, 0x7F7F7F7F, 0, 0x7F7F7F7F);
;     p1 = __builtin_amdgcn_mfma_scale_f32_32x32x64_f8f6f4(b1, qr[m], p1, 0, 0, 0, 0x7F7F7F7F, 0, 0x7F7F7F7F); }
; }
.Latt_mf_nold:
	s_waitcnt lgkmcnt(9)
	v_mfma_scale_f32_32x32x64_f8f6f4 v[64:79], v[128:135], v[112:119], v[64:79], v235, v201 op_sel_hi:[0,0,0]
	ds_read_b128 v[128:131], v220 offset:13312
	ds_read_b128 v[132:135], v220 offset:13328
	s_waitcnt lgkmcnt(9)
	v_mfma_scale_f32_32x32x64_f8f6f4 v[80:95], v[136:143], v[112:119], v[80:95], v235, v201 op_sel_hi:[0,0,0]
	ds_read_b128 v[136:139], v220 offset:19968
	ds_read_b128 v[140:143], v220 offset:19984
	s_nop 15
	s_nop 7

; __device__ __forceinline__ void partialSM(f32x16& p0, f32x16& p1, float& m_reg, float& mn, float& alpha) {
;   constexpr float C = SCALE * 1.4426950408889634f;
;   float pmax = p0[0]; for (int r = 1; r < 16; ++r) pmax = fmaxf(pmax, p0[r]); for (int r = 0; r < 16; ++r) pmax = fmaxf(pmax, p1[r]);
;   { auto rr = __builtin_amdgcn_permlane32_swap(__float_as_uint(pmax), __float_as_uint(pmax), false, false);
;     pmax = fmaxf(__uint_as_float(rr[0]), __uint_as_float(rr[1])); }
;   if (__builtin_expect(__all(pmax - m_reg <= THR / SCALE), 1)) { mn = m_reg; alpha = 1.f; }
;   else { mn = fmaxf(m_reg, pmax); alpha = __builtin_amdgcn_exp2f((m_reg - mn) * C); m_reg = mn; }
.Latt_m_nobar_0:
	v_max3_f32 v228, v64, v65, v66
	v_max3_f32 v229, v80, v81, v82
	v_max3_f32 v228, v228, v67, v68
	v_max3_f32 v229, v229, v83, v84
	v_max3_f32 v228, v228, v69, v70
	v_max3_f32 v229, v229, v85, v86
	v_max3_f32 v228, v228, v71, v72
	v_max3_f32 v229, v229, v87, v88
	v_max3_f32 v228, v228, v73, v74
	v_max3_f32 v229, v229, v89, v90
	v_max3_f32 v228, v228, v75, v76
	v_max3_f32 v229, v229, v91, v92
	v_max3_f32 v228, v228, v77, v78
	v_max3_f32 v229, v229, v93, v94
	v_max3_f32 v228, v228, v79, v95
	v_max_f32_e32 v228, v228, v229
	v_mov_b32_e32 v229, v228
	s_mov_b32 s5, 0
	s_nop 0
	v_permlane32_swap_b32_e32 v228, v229
	v_max_f32_e32 v228, v228, v229
	v_cmp_ge_f32_e32 vcc, s13, v228
	v_mov_b32_e32 v226, 1.0
	s_cmp_eq_u32 s6, 0
	s_cbranch_scc1 .Latt_rare
	s_cmp_eq_u64 vcc, exec
	s_cbranch_scc0 .Latt_rare

; __device__ __forceinline__ int ltid() { int t = threadIdx.x; asm volatile("" : "+v"(t)); return t; }
; __device__ __forceinline__ void qkt(f32x16& p0, f32x16& p1, const unsigned char* Ks, const i32x8* qr, int r32, int hi) {
;   p0 = f32x16{}; p1 = f32x16{};
; #pragma unroll
;   for (int m = 0; m < 3; ++m) { const int cb = m * 64 + hi * 32;
;     const u32x4 a0 = *reinterpret_cast<const u32x4*>(Ks + KSWZ(r32, cb)), a1 = *reinterpret_cast<const u32x4*>(Ks + KSWZ(r32, cb) + 16);
;     const u32x4 c0 = *reinterpret_cast<const u32x4*>(Ks + KSWZ(32 + r32, cb)), c1 = *reinterpret_cast<const u32x4*>(Ks + KSWZ(32 + r32, cb) + 16);
;     const i32x8 b0 = {(int)a0.x, (int)a0.y, (int)a0.z, (int)a0.w, (int)a1.x, (int)a1.y, (int)a1.z, (int)a1.w};
;     const i32x8 b1 = {(int)c0.x, (int)c0.y, (int)c0.z, (int)c0.w, (int)c1.x, (int)c1.y, (int)c1.z, (int)c1.w};
;     p0 = __builtin_amdgcn_mfma_scale_f32_32x32x64_f8f6f4(b0, qr[m], p0, 0, 0, 0, 0x7F7F7F7F, 0, 0x7F7F7F7F);
;     p1 = __builtin_amdgcn_mfma_scale_f32_32x32x64_f8f6f4(b1, qr[m], p1, 0, 0, 0, 0x7F7F7F7F, 0, 0x7F7F7F7F); }
; }
; __device__ __forceinline__ void pv_d0(f32x16* o, const unsigned char* Vs, const i32x8& pa, int r32, int hi) {
; #pragma unroll
;   for (int d0 = 0; d0 < 4; ++d0) { const unsigned char* vp = Vs + (32 * d0 + r32) * 80 + hi * 32;
;     const u32x4 a0 = *reinterpret_cast<const u32x4*>(vp), a1 = *reinterpret_cast<const u32x4*>(vp + 16);
;     const i32x8 vb = {(int)a0.x, (int)a0.y, (int)a0.z, (int)a0.w, (int)a1.x, (int)a1.y, (int)a1.z, (int)a1.w};
;     o[d0] = __builtin_amdgcn_mfma_scale_f32_32x32x64_f8f6f4(pa, vb, o[d0], 0, 0, 0, 0x7A7A7A7A, 0, 0x7F7F7F7F); }
; }
; __device__ __forceinline__ void attn_body(const unsigned char* __restrict__ Qb, const unsigned char* __restrict__ Kh, const unsigned char* __restrict__ Vt,
;                                           bf16_t* __restrict__ Ob, int seq, char* lds) {
;   const int tid = ltid(), wid = tid >> 6, lane = tid & 63, r32 = lane & 31, hi = lane >> 5;
;   unsigned char* V_lds = (unsigned char*)lds; unsigned char* K_lds = (unsigned char*)(lds + 3 * SHM_V);
;   float* ws = (float*)(lds + 3 * SHM_V + 3 * SHM_K) + wid * 64; float* li_l = ws; float* al_l = ws + 32;
;   float m_reg = -1e30f, l_reg = 0; f32x16 o[4] = {}; i32x8 qr[3];
;   const unsigned char* Qw = Qb + (long)(wid * QBLK + r32) * 192 + hi * 32;
; #pragma unroll
.Latt_v_nobar_0:
	s_add_u32 s6, s6, 1
	s_add_u32 s4, s6, 2
	ds_read_b128 v[176:179], v221 offset:0
	ds_read_b128 v[180:183], v221 offset:16
	ds_read_b128 v[184:187], v221 offset:2560
	ds_read_b128 v[188:191], v221 offset:2576
	s_waitcnt lgkmcnt(4)
	v_mfma_scale_f32_32x32x64_f8f6f4 v[64:79], v[128:135], v[96:103], v[160:175], v235, v201 op_sel_hi:[0,0,0]
	ds_read_b128 v[128:131], v220 offset:13440
	ds_read_b128 v[132:135], v220 offset:13456
	v_mfma_scale_f32_32x32x64_f8f6f4 v[80:95], v[136:143], v[96:103], v[160:175], v235, v201 op_sel_hi:[0,0,0]
	ds_read_b128 v[136:139], v220 offset:20096
	ds_read_b128 v[140:143], v220 offset:20112
	s_cmp_lt_u32 s4, 128
	s_cbranch_scc0 .Latt_ms1_nowr
	v_add_u32_e32 v228, 30720, v217
	s_waitcnt vmcnt(0)
	ds_write2_b32 v228, v202, v204 offset1:1
	ds_write2_b32 v228, v203, v205 offset0:8 offset1:9
	ds_write_b128 v218, v[206:209] offset:39936
	s_cmp_lt_u32 s12, 4
	s_cbranch_scc0 .Latt_ms1_w1
	ds_write_b128 v219, v[210:213] offset:39936
.Latt_ms1_w1:
.Latt_ms1_nowr:
	v_mfma_scale_f32_32x32x64_f8f6f4 v[64:79], v[144:151], v[104:111], v[64:79], v235, v201 op_sel_hi:[0,0,0]
	ds_read_b128 v[144:147], v220 offset:26688
	ds_read_b128 v[148:151], v220 offset:26704
	v_mfma_scale_f32_32x32x64_f8f6f4 v[80:95], v[152:159], v[104:111], v[80:95], v235, v201 op_sel_hi:[0,0,0]
	ds_read_b128 v[152:155], v220 offset:33344
	ds_read_b128 v[156:159], v220 offset:33360
	s_cmp_lt_u32 s4, 127
	s_cbranch_scc0 .Latt_ms1_nold
	global_load_dwordx4 v[202:205], v216, s[10:11]
	global_load_dwordx4 v[206:209], v214, s[8:9]
	s_cmp_lt_u32 s12, 4
	s_cbranch_scc0 .Latt_ms1_l1
	global_load_dwordx4 v[210:213], v215, s[8:9]

; __device__ __forceinline__ void qkt(f32x16& p0, f32x16& p1, const unsigned char* Ks, const i32x8* qr, int r32, int hi) {
;   p0 = f32x16{}; p1 = f32x16{};
; #pragma unroll
;   for (int m = 0; m < 3; ++m) { const int cb = m * 64 + hi * 32;
;     const u32x4 a0 = *reinterpret_cast<const u32x4*>(Ks + KSWZ(r32, cb)), a1 = *reinterpret_cast<const u32x4*>(Ks + KSWZ(r32, cb) + 16);
;     const u32x4 c0 = *reinterpret_cast<const u32x4*>(Ks + KSWZ(32 + r32, cb)), c1 = *reinterpret_cast<const u32x4*>(Ks + KSWZ(32 + r32, cb) + 16);
;     const i32x8 b0 = {(int)a0.x, (int)a0.y, (int)a0.z, (int)a0.w, (int)a1.x, (int)a1.y, (int)a1.z, (int)a1.w};
;     const i32x8 b1 = {(int)c0.x, (int)c0.y, (int)c0.z, (int)c0.w, (int)c1.x, (int)c1.y, (int)c1.z, (int)c1.w};
;     p0 = __builtin_amdgcn_mfma_scale_f32_32x32x64_f8f6f4(b0, qr[m], p0, 0, 0, 0, 0x7F7F7F7F, 0, 0x7F7F7F7F);
;     p1 = __builtin_amdgcn_mfma_scale_f32_32x32x64_f8f6f4(b1, qr[m], p1, 0, 0, 0, 0x7F7F7F7F, 0, 0x7F7F7F7F); }
; }
; __device__ __forceinline__ void pv_d0(f32x16* o, const unsigned char* Vs, const i32x8& pa, int r32, int hi) {
; #pragma unroll
;   for (int d0 = 0; d0 < 4; ++d0) { const unsigned char* vp = Vs + (32 * d0 + r32) * 80 + hi * 32;
;     const u32x4 a0 = *reinterpret_cast<const u32x4*>(vp), a1 = *reinterpret_cast<const u32x4*>(vp + 16);
;     const i32x8 vb = {(int)a0.x, (int)a0.y, (int)a0.z, (int)a0.w, (int)a1.x, (int)a1.y, (int)a1.z, (int)a1.w};
;     o[d0] = __builtin_amdgcn_mfma_scale_f32_32x32x64_f8f6f4(pa, vb, o[d0], 0, 0, 0, 0x7A7A7A7A, 0, 0x7F7F7F7F); }
; }
.Latt_ms1_nold:
	s_waitcnt lgkmcnt(9)
	v_mfma_scale_f32_32x32x64_f8f6f4 v[64:79], v[128:135], v[112:119], v[64:79], v235, v201 op_sel_hi:[0,0,0]
	ds_read_b128 v[128:131], v220 offset:26624
	ds_read_b128 v[132:135], v220 offset:26640
	s_waitcnt lgkmcnt(9)
	v_mfma_scale_f32_32x32x64_f8f6f4 v[80:95], v[136:143], v[112:119], v[80:95], v235, v201 op_sel_hi:[0,0,0]
	ds_read_b128 v[136:139], v220 offset:33280
	ds_read_b128 v[140:143], v220 offset:33296
	s_waitcnt lgkmcnt(8)
	v_mfma_scale_f32_32x32x64_f8f6f4 v[0:15], v[120:127], v[176:183], v[0:15], v237, v235 op_sel_hi:[0,0,0]
	ds_read_b128 v[176:179], v221 offset:5120
	ds_read_b128 v[180:183], v221 offset:5136
	v_mfma_scale_f32_32x32x64_f8f6f4 v[16:31], v[120:127], v[184:191], v[16:31], v237, v235 op_sel_hi:[0,0,0]
	ds_read_b128 v[184:187], v221 offset:7680
	ds_read_b128 v[188:191], v221 offset:7696
	s_waitcnt lgkmcnt(2)
	v_mfma_scale_f32_32x32x64_f8f6f4 v[32:47], v[120:127], v[176:183], v[32:47], v237, v235 op_sel_hi:[0,0,0]
	s_waitcnt lgkmcnt(0)
	v_mfma_scale_f32_32x32x64_f8f6f4 v[48:63], v[120:127], v[184:191], v[48:63], v237, v235 op_sel_hi:[0,0,0]

; __device__ __forceinline__ void partialSM(f32x16& p0, f32x16& p1, float& m_reg, float& mn, float& alpha) {
;   constexpr float C = SCALE * 1.4426950408889634f;
;   float pmax = p0[0]; for (int r = 1; r < 16; ++r) pmax = fmaxf(pmax, p0[r]); for (int r = 0; r < 16; ++r) pmax = fmaxf(pmax, p1[r]);
;   { auto rr = __builtin_amdgcn_permlane32_swap(__float_as_uint(pmax), __float_as_uint(pmax), false, false);
;     pmax = fmaxf(__uint_as_float(rr[0]), __uint_as_float(rr[1])); }
;   if (__builtin_expect(__all(pmax - m_reg <= THR / SCALE), 1)) { mn = m_reg; alpha = 1.f; }
;   else { mn = fmaxf(m_reg, pmax); alpha = __builtin_amdgcn_exp2f((m_reg - mn) * C); m_reg = mn; }
.Latt_m_nobar_1:
	v_max3_f32 v228, v64, v65, v66
	v_max3_f32 v229, v80, v81, v82
	v_max3_f32 v228, v228, v67, v68
	v_max3_f32 v229, v229, v83, v84
	v_max3_f32 v228, v228, v69, v70
	v_max3_f32 v229, v229, v85, v86
	v_max3_f32 v228, v228, v71, v72
	v_max3_f32 v229, v229, v87, v88
	v_max3_f32 v228, v228, v73, v74
	v_max3_f32 v229, v229, v89, v90
	v_max3_f32 v228, v228, v75, v76
	v_max3_f32 v229, v229, v91, v92
	v_max3_f32 v228, v228, v77, v78
	v_max3_f32 v229, v229, v93, v94
	v_max3_f32 v228, v228, v79, v95
	v_max_f32_e32 v228, v228, v229
	v_mov_b32_e32 v229, v228
	s_mov_b32 s5, 1
	s_nop 0
	v_permlane32_swap_b32_e32 v228, v229
	v_max_f32_e32 v228, v228, v229
	v_cmp_ge_f32_e32 vcc, s13, v228
	v_mov_b32_e32 v226, 1.0
	s_cmp_eq_u64 vcc, exec
	s_cbranch_scc0 .Latt_rare

; __device__ __forceinline__ int ltid() { int t = threadIdx.x; asm volatile("" : "+v"(t)); return t; }
; __device__ __forceinline__ void qkt(f32x16& p0, f32x16& p1, const unsigned char* Ks, const i32x8* qr, int r32, int hi) {
;   p0 = f32x16{}; p1 = f32x16{};
; #pragma unroll
;   for (int m = 0; m < 3; ++m) { const int cb = m * 64 + hi * 32;
;     const u32x4 a0 = *reinterpret_cast<const u32x4*>(Ks + KSWZ(r32, cb)), a1 = *reinterpret_cast<const u32x4*>(Ks + KSWZ(r32, cb) + 16);
;     const u32x4 c0 = *reinterpret_cast<const u32x4*>(Ks + KSWZ(32 + r32, cb)), c1 = *reinterpret_cast<const u32x4*>(Ks + KSWZ(32 + r32, cb) + 16);
;     const i32x8 b0 = {(int)a0.x, (int)a0.y, (int)a0.z, (int)a0.w, (int)a1.x, (int)a1.y, (int)a1.z, (int)a1.w};
;     const i32x8 b1 = {(int)c0.x, (int)c0.y, (int)c0.z, (int)c0.w, (int)c1.x, (int)c1.y, (int)c1.z, (int)c1.w};
;     p0 = __builtin_amdgcn_mfma_scale_f32_32x32x64_f8f6f4(b0, qr[m], p0, 0, 0, 0, 0x7F7F7F7F, 0, 0x7F7F7F7F);
;     p1 = __builtin_amdgcn_mfma_scale_f32_32x32x64_f8f6f4(b1, qr[m], p1, 0, 0, 0, 0x7F7F7F7F, 0, 0x7F7F7F7F); }
; }
; __device__ __forceinline__ void pv_d0(f32x16* o, const unsigned char* Vs, const i32x8& pa, int r32, int hi) {
; #pragma unroll
;   for (int d0 = 0; d0 < 4; ++d0) { const unsigned char* vp = Vs + (32 * d0 + r32) * 80 + hi * 32;
;     const u32x4 a0 = *reinterpret_cast<const u32x4*>(vp), a1 = *reinterpret_cast<const u32x4*>(vp + 16);
;     const i32x8 vb = {(int)a0.x, (int)a0.y, (int)a0.z, (int)a0.w, (int)a1.x, (int)a1.y, (int)a1.z, (int)a1.w};
;     o[d0] = __builtin_amdgcn_mfma_scale_f32_32x32x64_f8f6f4(pa, vb, o[d0], 0, 0, 0, 0x7A7A7A7A, 0, 0x7F7F7F7F); }
; }
; __device__ __forceinline__ void attn_body(const unsigned char* __restrict__ Qb, const unsigned char* __restrict__ Kh, const unsigned char* __restrict__ Vt,
;                                           bf16_t* __restrict__ Ob, int seq, char* lds) {
;   const int tid = ltid(), wid = tid >> 6, lane = tid & 63, r32 = lane & 31, hi = lane >> 5;
;   unsigned char* V_lds = (unsigned char*)lds; unsigned char* K_lds = (unsigned char*)(lds + 3 * SHM_V);
;   float* ws = (float*)(lds + 3 * SHM_V + 3 * SHM_K) + wid * 64; float* li_l = ws; float* al_l = ws + 32;
;   float m_reg = -1e30f, l_reg = 0; f32x16 o[4] = {}; i32x8 qr[3];
;   const unsigned char* Qw = Qb + (long)(wid * QBLK + r32) * 192 + hi * 32;
; #pragma unroll
.Latt_v_nobar_1:
	s_add_u32 s6, s6, 1
	s_add_u32 s4, s6, 2
	ds_read_b128 v[176:179], v221 offset:10240
	ds_read_b128 v[180:183], v221 offset:10256
	ds_read_b128 v[184:187], v221 offset:12800
	ds_read_b128 v[188:191], v221 offset:12816
	s_waitcnt lgkmcnt(4)
	v_mfma_scale_f32_32x32x64_f8f6f4 v[64:79], v[128:135], v[96:103], v[160:175], v235, v201 op_sel_hi:[0,0,0]
	ds_read_b128 v[128:131], v220 offset:26752
	ds_read_b128 v[132:135], v220 offset:26768
	v_mfma_scale_f32_32x32x64_f8f6f4 v[80:95], v[136:143], v[96:103], v[160:175], v235, v201 op_sel_hi:[0,0,0]
	ds_read_b128 v[136:139], v220 offset:33408
	ds_read_b128 v[140:143], v220 offset:33424
	s_cmp_lt_u32 s4, 128
	s_cbranch_scc0 .Latt_ms2_nowr
	s_waitcnt vmcnt(0)
	ds_write2_b32 v217, v202, v204 offset1:1
	ds_write2_b32 v217, v203, v205 offset0:8 offset1:9
	ds_write_b128 v218, v[206:209] offset:0
	s_cmp_lt_u32 s12, 4
	s_cbranch_scc0 .Latt_ms2_w1
	ds_write_b128 v219, v[210:213] offset:0
.Latt_ms2_w1:
.Latt_ms2_nowr:
	v_mfma_scale_f32_32x32x64_f8f6f4 v[64:79], v[144:151], v[104:111], v[64:79], v235, v201 op_sel_hi:[0,0,0]
	ds_read_b128 v[144:147], v220 offset:40000
	ds_read_b128 v[148:151], v220 offset:40016
	v_mfma_scale_f32_32x32x64_f8f6f4 v[80:95], v[152:159], v[104:111], v[80:95], v235, v201 op_sel_hi:[0,0,0]
	ds_read_b128 v[152:155], v220 offset:46656
	ds_read_b128 v[156:159], v220 offset:46672
	s_cmp_lt_u32 s4, 127
	s_cbranch_scc0 .Latt_ms2_nold
	global_load_dwordx4 v[202:205], v216, s[10:11]
	global_load_dwordx4 v[206:209], v214, s[8:9]
	s_cmp_lt_u32 s12, 4
	s_cbranch_scc0 .Latt_ms2_l1
	global_load_dwordx4 v[210:213], v215, s[8:9]

; __device__ __forceinline__ void qkt(f32x16& p0, f32x16& p1, const unsigned char* Ks, const i32x8* qr, int r32, int hi) {
;   p0 = f32x16{}; p1 = f32x16{};
; #pragma unroll
;   for (int m = 0; m < 3; ++m) { const int cb = m * 64 + hi * 32;
;     const u32x4 a0 = *reinterpret_cast<const u32x4*>(Ks + KSWZ(r32, cb)), a1 = *reinterpret_cast<const u32x4*>(Ks + KSWZ(r32, cb) + 16);
;     const u32x4 c0 = *reinterpret_cast<const u32x4*>(Ks + KSWZ(32 + r32, cb)), c1 = *reinterpret_cast<const u32x4*>(Ks + KSWZ(32 + r32, cb) + 16);
;     const i32x8 b0 = {(int)a0.x, (int)a0.y, (int)a0.z, (int)a0.w, (int)a1.x, (int)a1.y, (int)a1.z, (int)a1.w};
;     const i32x8 b1 = {(int)c0.x, (int)c0.y, (int)c0.z, (int)c0.w, (int)c1.x, (int)c1.y, (int)c1.z, (int)c1.w};
;     p0 = __builtin_amdgcn_mfma_scale_f32_32x32x64_f8f6f4(b0, qr[m], p0, 0, 0, 0, 0x7F7F7F7F, 0, 0x7F7F7F7F);
;     p1 = __builtin_amdgcn_mfma_scale_f32_32x32x64_f8f6f4(b1, qr[m], p1, 0, 0, 0, 0x7F7F7F7F, 0, 0x7F7F7F7F); }
; }
; __device__ __forceinline__ void pv_d0(f32x16* o, const unsigned char* Vs, const i32x8& pa, int r32, int hi) {
; #pragma unroll
;   for (int d0 = 0; d0 < 4; ++d0) { const unsigned char* vp = Vs + (32 * d0 + r32) * 80 + hi * 32;
;     const u32x4 a0 = *reinterpret_cast<const u32x4*>(vp), a1 = *reinterpret_cast<const u32x4*>(vp + 16);
;     const i32x8 vb = {(int)a0.x, (int)a0.y, (int)a0.z, (int)a0.w, (int)a1.x, (int)a1.y, (int)a1.z, (int)a1.w};
;     o[d0] = __builtin_amdgcn_mfma_scale_f32_32x32x64_f8f6f4(pa, vb, o[d0], 0, 0, 0, 0x7A7A7A7A, 0, 0x7F7F7F7F); }
; }
.Latt_ms2_nold:
	s_waitcnt lgkmcnt(9)
	v_mfma_scale_f32_32x32x64_f8f6f4 v[64:79], v[128:135], v[112:119], v[64:79], v235, v201 op_sel_hi:[0,0,0]
	ds_read_b128 v[128:131], v220 offset:39936
	ds_read_b128 v[132:135], v220 offset:39952
	s_waitcnt lgkmcnt(9)
	v_mfma_scale_f32_32x32x64_f8f6f4 v[80:95], v[136:143], v[112:119], v[80:95], v235, v201 op_sel_hi:[0,0,0]
	ds_read_b128 v[136:139], v220 offset:46592
	ds_read_b128 v[140:143], v220 offset:46608
	s_waitcnt lgkmcnt(8)
	v_mfma_scale_f32_32x32x64_f8f6f4 v[0:15], v[120:127], v[176:183], v[0:15], v237, v235 op_sel_hi:[0,0,0]
	ds_read_b128 v[176:179], v221 offset:15360
	ds_read_b128 v[180:183], v221 offset:15376
	v_mfma_scale_f32_32x32x64_f8f6f4 v[16:31], v[120:127], v[184:191], v[16:31], v237, v235 op_sel_hi:[0,0,0]
	ds_read_b128 v[184:187], v221 offset:17920
	ds_read_b128 v[188:191], v221 offset:17936
	s_waitcnt lgkmcnt(2)
	v_mfma_scale_f32_32x32x64_f8f6f4 v[32:47], v[120:127], v[176:183], v[32:47], v237, v235 op_sel_hi:[0,0,0]
	s_waitcnt lgkmcnt(0)
	v_mfma_scale_f32_32x32x64_f8f6f4 v[48:63], v[120:127], v[184:191], v[48:63], v237, v235 op_sel_hi:[0,0,0]

; __device__ __forceinline__ void partialSM(f32x16& p0, f32x16& p1, float& m_reg, float& mn, float& alpha) {
;   constexpr float C = SCALE * 1.4426950408889634f;
;   float pmax = p0[0]; for (int r = 1; r < 16; ++r) pmax = fmaxf(pmax, p0[r]); for (int r = 0; r < 16; ++r) pmax = fmaxf(pmax, p1[r]);
;   { auto rr = __builtin_amdgcn_permlane32_swap(__float_as_uint(pmax), __float_as_uint(pmax), false, false);
;     pmax = fmaxf(__uint_as_float(rr[0]), __uint_as_float(rr[1])); }
;   if (__builtin_expect(__all(pmax - m_reg <= THR / SCALE), 1)) { mn = m_reg; alpha = 1.f; }
;   else { mn = fmaxf(m_reg, pmax); alpha = __builtin_amdgcn_exp2f((m_reg - mn) * C); m_reg = mn; }
.Latt_m_nobar_2:
	v_max3_f32 v228, v64, v65, v66
	v_max3_f32 v229, v80, v81, v82
	v_max3_f32 v228, v228, v67, v68
	v_max3_f32 v229, v229, v83, v84
	v_max3_f32 v228, v228, v69, v70
	v_max3_f32 v229, v229, v85, v86
	v_max3_f32 v228, v228, v71, v72
	v_max3_f32 v229, v229, v87, v88
	v_max3_f32 v228, v228, v73, v74
	v_max3_f32 v229, v229, v89, v90
	v_max3_f32 v228, v228, v75, v76
	v_max3_f32 v229, v229, v91, v92
	v_max3_f32 v228, v228, v77, v78
	v_max3_f32 v229, v229, v93, v94
	v_max3_f32 v228, v228, v79, v95
	v_max_f32_e32 v228, v228, v229
	v_mov_b32_e32 v229, v228
	s_mov_b32 s5, 2
	s_nop 0
	v_permlane32_swap_b32_e32 v228, v229
	v_max_f32_e32 v228, v228, v229
	v_cmp_ge_f32_e32 vcc, s13, v228
	v_mov_b32_e32 v226, 1.0
	s_cmp_eq_u64 vcc, exec
	s_cbranch_scc0 .Latt_rare

; __device__ __forceinline__ int ltid() { int t = threadIdx.x; asm volatile("" : "+v"(t)); return t; }
; __device__ __forceinline__ void qkt(f32x16& p0, f32x16& p1, const unsigned char* Ks, const i32x8* qr, int r32, int hi) {
;   p0 = f32x16{}; p1 = f32x16{};
; #pragma unroll
;   for (int m = 0; m < 3; ++m) { const int cb = m * 64 + hi * 32;
;     const u32x4 a0 = *reinterpret_cast<const u32x4*>(Ks + KSWZ(r32, cb)), a1 = *reinterpret_cast<const u32x4*>(Ks + KSWZ(r32, cb) + 16);
;     const u32x4 c0 = *reinterpret_cast<const u32x4*>(Ks + KSWZ(32 + r32, cb)), c1 = *reinterpret_cast<const u32x4*>(Ks + KSWZ(32 + r32, cb) + 16);
;     const i32x8 b0 = {(int)a0.x, (int)a0.y, (int)a0.z, (int)a0.w, (int)a1.x, (int)a1.y, (int)a1.z, (int)a1.w};
;     const i32x8 b1 = {(int)c0.x, (int)c0.y, (int)c0.z, (int)c0.w, (int)c1.x, (int)c1.y, (int)c1.z, (int)c1.w};
;     p0 = __builtin_amdgcn_mfma_scale_f32_32x32x64_f8f6f4(b0, qr[m], p0, 0, 0, 0, 0x7F7F7F7F, 0, 0x7F7F7F7F);
;     p1 = __builtin_amdgcn_mfma_scale_f32_32x32x64_f8f6f4(b1, qr[m], p1, 0, 0, 0, 0x7F7F7F7F, 0, 0x7F7F7F7F); }
; }
; __device__ __forceinline__ void pv_d0(f32x16* o, const unsigned char* Vs, const i32x8& pa, int r32, int hi) {
; #pragma unroll
;   for (int d0 = 0; d0 < 4; ++d0) { const unsigned char* vp = Vs + (32 * d0 + r32) * 80 + hi * 32;
;     const u32x4 a0 = *reinterpret_cast<const u32x4*>(vp), a1 = *reinterpret_cast<const u32x4*>(vp + 16);
;     const i32x8 vb = {(int)a0.x, (int)a0.y, (int)a0.z, (int)a0.w, (int)a1.x, (int)a1.y, (int)a1.z, (int)a1.w};
;     o[d0] = __builtin_amdgcn_mfma_scale_f32_32x32x64_f8f6f4(pa, vb, o[d0], 0, 0, 0, 0x7A7A7A7A, 0, 0x7F7F7F7F); }
; }
; __device__ __forceinline__ void attn_body(const unsigned char* __restrict__ Qb, const unsigned char* __restrict__ Kh, const unsigned char* __restrict__ Vt,
;                                           bf16_t* __restrict__ Ob, int seq, char* lds) {
;   const int tid = ltid(), wid = tid >> 6, lane = tid & 63, r32 = lane & 31, hi = lane >> 5;
;   unsigned char* V_lds = (unsigned char*)lds; unsigned char* K_lds = (unsigned char*)(lds + 3 * SHM_V);
;   float* ws = (float*)(lds + 3 * SHM_V + 3 * SHM_K) + wid * 64; float* li_l = ws; float* al_l = ws + 32;
;   float m_reg = -1e30f, l_reg = 0; f32x16 o[4] = {}; i32x8 qr[3];
;   const unsigned char* Qw = Qb + (long)(wid * QBLK + r32) * 192 + hi * 32;
; #pragma unroll
.Latt_v_nobar_2:
	s_add_u32 s6, s6, 1
	s_add_u32 s4, s6, 2
	ds_read_b128 v[176:179], v221 offset:20480
	ds_read_b128 v[180:183], v221 offset:20496
	ds_read_b128 v[184:187], v221 offset:23040
	ds_read_b128 v[188:191], v221 offset:23056
	s_waitcnt lgkmcnt(4)
	v_mfma_scale_f32_32x32x64_f8f6f4 v[64:79], v[128:135], v[96:103], v[160:175], v235, v201 op_sel_hi:[0,0,0]
	ds_read_b128 v[128:131], v220 offset:40064
	ds_read_b128 v[132:135], v220 offset:40080
	v_mfma_scale_f32_32x32x64_f8f6f4 v[80:95], v[136:143], v[96:103], v[160:175], v235, v201 op_sel_hi:[0,0,0]
	ds_read_b128 v[136:139], v220 offset:46720
	ds_read_b128 v[140:143], v220 offset:46736
	s_cmp_lt_u32 s4, 128
	s_cbranch_scc0 .Latt_ms3_nowr
	s_waitcnt vmcnt(0)
	ds_write2_b32 v224, v202, v204 offset1:1
	ds_write2_b32 v224, v203, v205 offset0:8 offset1:9
	ds_write_b128 v218, v[206:209] offset:13312
	s_cmp_lt_u32 s12, 4
	s_cbranch_scc0 .Latt_ms3_w1
	ds_write_b128 v219, v[210:213] offset:13312
.Latt_ms3_w1:
.Latt_ms3_nowr:
	v_mfma_scale_f32_32x32x64_f8f6f4 v[64:79], v[144:151], v[104:111], v[64:79], v235, v201 op_sel_hi:[0,0,0]
	ds_read_b128 v[144:147], v220 offset:64
	ds_read_b128 v[148:151], v220 offset:80
	v_mfma_scale_f32_32x32x64_f8f6f4 v[80:95], v[152:159], v[104:111], v[80:95], v235, v201 op_sel_hi:[0,0,0]
	ds_read_b128 v[152:155], v220 offset:6720
	ds_read_b128 v[156:159], v220 offset:6736
	s_cmp_lt_u32 s4, 127
	s_cbranch_scc0 .Latt_ms3_nold
	global_load_dwordx4 v[202:205], v216, s[10:11]
	global_load_dwordx4 v[206:209], v214, s[8:9]
	s_cmp_lt_u32 s12, 4
	s_cbranch_scc0 .Latt_ms3_l1
	global_load_dwordx4 v[210:213], v215, s[8:9]

; __device__ __forceinline__ void qkt(f32x16& p0, f32x16& p1, const unsigned char* Ks, const i32x8* qr, int r32, int hi) {
;   p0 = f32x16{}; p1 = f32x16{};
; #pragma unroll
;   for (int m = 0; m < 3; ++m) { const int cb = m * 64 + hi * 32;
;     const u32x4 a0 = *reinterpret_cast<const u32x4*>(Ks + KSWZ(r32, cb)), a1 = *reinterpret_cast<const u32x4*>(Ks + KSWZ(r32, cb) + 16);
;     const u32x4 c0 = *reinterpret_cast<const u32x4*>(Ks + KSWZ(32 + r32, cb)), c1 = *reinterpret_cast<const u32x4*>(Ks + KSWZ(32 + r32, cb) + 16);
;     const i32x8 b0 = {(int)a0.x, (int)a0.y, (int)a0.z, (int)a0.w, (int)a1.x, (int)a1.y, (int)a1.z, (int)a1.w};
;     const i32x8 b1 = {(int)c0.x, (int)c0.y, (int)c0.z, (int)c0.w, (int)c1.x, (int)c1.y, (int)c1.z, (int)c1.w};
;     p0 = __builtin_amdgcn_mfma_scale_f32_32x32x64_f8f6f4(b0, qr[m], p0, 0, 0, 0, 0x7F7F7F7F, 0, 0x7F7F7F7F);
;     p1 = __builtin_amdgcn_mfma_scale_f32_32x32x64_f8f6f4(b1, qr[m], p1, 0, 0, 0, 0x7F7F7F7F, 0, 0x7F7F7F7F); }
; }
; __device__ __forceinline__ void pv_d0(f32x16* o, const unsigned char* Vs, const i32x8& pa, int r32, int hi) {
; #pragma unroll
;   for (int d0 = 0; d0 < 4; ++d0) { const unsigned char* vp = Vs + (32 * d0 + r32) * 80 + hi * 32;
;     const u32x4 a0 = *reinterpret_cast<const u32x4*>(vp), a1 = *reinterpret_cast<const u32x4*>(vp + 16);
;     const i32x8 vb = {(int)a0.x, (int)a0.y, (int)a0.z, (int)a0.w, (int)a1.x, (int)a1.y, (int)a1.z, (int)a1.w};
;     o[d0] = __builtin_amdgcn_mfma_scale_f32_32x32x64_f8f6f4(pa, vb, o[d0], 0, 0, 0, 0x7A7A7A7A, 0, 0x7F7F7F7F); }
; }
.Latt_ms3_nold:
	s_waitcnt lgkmcnt(9)
	v_mfma_scale_f32_32x32x64_f8f6f4 v[64:79], v[128:135], v[112:119], v[64:79], v235, v201 op_sel_hi:[0,0,0]
	ds_read_b128 v[128:131], v220 offset:0
	ds_read_b128 v[132:135], v220 offset:16
	s_waitcnt lgkmcnt(9)
	v_mfma_scale_f32_32x32x64_f8f6f4 v[80:95], v[136:143], v[112:119], v[80:95], v235, v201 op_sel_hi:[0,0,0]
	ds_read_b128 v[136:139], v220 offset:6656
	ds_read_b128 v[140:143], v220 offset:6672
	s_waitcnt lgkmcnt(8)
	v_mfma_scale_f32_32x32x64_f8f6f4 v[0:15], v[120:127], v[176:183], v[0:15], v237, v235 op_sel_hi:[0,0,0]
	ds_read_b128 v[176:179], v221 offset:25600
	ds_read_b128 v[180:183], v221 offset:25616
	v_mfma_scale_f32_32x32x64_f8f6f4 v[16:31], v[120:127], v[184:191], v[16:31], v237, v235 op_sel_hi:[0,0,0]
	ds_read_b128 v[184:187], v221 offset:28160
	ds_read_b128 v[188:191], v221 offset:28176
	s_waitcnt lgkmcnt(2)
	v_mfma_scale_f32_32x32x64_f8f6f4 v[32:47], v[120:127], v[176:183], v[32:47], v237, v235 op_sel_hi:[0,0,0]
	s_waitcnt lgkmcnt(0)
	v_mfma_scale_f32_32x32x64_f8f6f4 v[48:63], v[120:127], v[184:191], v[48:63], v237, v235 op_sel_hi:[0,0,0]

; __device__ __forceinline__ void partialSM(f32x16& p0, f32x16& p1, float& m_reg, float& mn, float& alpha) {
;   constexpr float C = SCALE * 1.4426950408889634f;
;   float pmax = p0[0]; for (int r = 1; r < 16; ++r) pmax = fmaxf(pmax, p0[r]); for (int r = 0; r < 16; ++r) pmax = fmaxf(pmax, p1[r]);
;   { auto rr = __builtin_amdgcn_permlane32_swap(__float_as_uint(pmax), __float_as_uint(pmax), false, false);
;     pmax = fmaxf(__uint_as_float(rr[0]), __uint_as_float(rr[1])); }
;   if (__builtin_expect(__all(pmax - m_reg <= THR / SCALE), 1)) { mn = m_reg; alpha = 1.f; }
;   else { mn = fmaxf(m_reg, pmax); alpha = __builtin_amdgcn_exp2f((m_reg - mn) * C); m_reg = mn; }
.Latt_m_nobar_3:
	v_max3_f32 v228, v64, v65, v66
	v_max3_f32 v229, v80, v81, v82
	v_max3_f32 v228, v228, v67, v68
	v_max3_f32 v229, v229, v83, v84
	v_max3_f32 v228, v228, v69, v70
	v_max3_f32 v229, v229, v85, v86
	v_max3_f32 v228, v228, v71, v72
	v_max3_f32 v229, v229, v87, v88
	v_max3_f32 v228, v228, v73, v74
	v_max3_f32 v229, v229, v89, v90
	v_max3_f32 v228, v228, v75, v76
	v_max3_f32 v229, v229, v91, v92
	v_max3_f32 v228, v228, v77, v78
	v_max3_f32 v229, v229, v93, v94
	v_max3_f32 v228, v228, v79, v95
	v_max_f32_e32 v228, v228, v229
	v_mov_b32_e32 v229, v228
	s_mov_b32 s5, 3
	s_nop 0
	v_permlane32_swap_b32_e32 v228, v229
	v_max_f32_e32 v228, v228, v229
	v_cmp_ge_f32_e32 vcc, s13, v228
	v_mov_b32_e32 v226, 1.0
	s_cmp_eq_u64 vcc, exec
	s_cbranch_scc0 .Latt_rare

; __device__ __forceinline__ bf16_t f2bf(float f) { return (bf16_t)(cvt_pk_bf16(f, 0.f) & 0xffffu); }
; #define SBAR() __builtin_amdgcn_sched_barrier(0)
; __device__ __forceinline__ int crow(int r, int hi) { return (r & 3) + 8 * (r >> 2) + 4 * hi; }
; __device__ __forceinline__ void attn_body(const unsigned char* __restrict__ Qb, const unsigned char* __restrict__ Kh, const unsigned char* __restrict__ Vt,
;                                           bf16_t* __restrict__ Ob, int seq, char* lds) {
;     ...
;   STEP(NT - 1, pB0, pB1, mnB, alB, pA0, pA1, alA);
;   finishSM(pB0, pB1, alB, l_reg, pa); SBAR();
;   pv_d0(o, V_lds + sP * SHM_V, pa, r32, hi);
;     ...
;   if (hi == 0) li_l[r32] = l_reg; asm volatile("s_waitcnt lgkmcnt(0)" ::: "memory");
;   float rli[16];
; #pragma unroll
;   for (int r = 0; r < 16; ++r) rli[r] = 32.f * __builtin_amdgcn_rcpf(li_l[crow(r, hi)]);
;   bf16_t* Ow = Ob + (long)(wid * QBLK) * LDO;
; #pragma unroll
;   for (int r = 0; r < 16; ++r) { int orow = crow(r, hi);
;     for (int d0 = 0; d0 < 4; ++d0) Ow[(long)orow * LDO + d0 * 32 + r32] = f2bf(o[d0][r] * rli[r]); }
.Latt_tail:
	ds_read_b128 v[176:179], v221 offset:30720
	ds_read_b128 v[180:183], v221 offset:30736
	ds_read_b128 v[184:187], v221 offset:33280
	ds_read_b128 v[188:191], v221 offset:33296
	s_waitcnt lgkmcnt(2)
	v_mfma_scale_f32_32x32x64_f8f6f4 v[0:15], v[120:127], v[176:183], v[0:15], v237, v235 op_sel_hi:[0,0,0]
	ds_read_b128 v[176:179], v221 offset:35840
	ds_read_b128 v[180:183], v221 offset:35856
	s_waitcnt lgkmcnt(2)
	v_mfma_scale_f32_32x32x64_f8f6f4 v[16:31], v[120:127], v[184:191], v[16:31], v237, v235 op_sel_hi:[0,0,0]
	ds_read_b128 v[184:187], v221 offset:38400
	ds_read_b128 v[188:191], v221 offset:38416
	s_waitcnt lgkmcnt(2)
	v_mfma_scale_f32_32x32x64_f8f6f4 v[32:47], v[120:127], v[176:183], v[32:47], v237, v235 op_sel_hi:[0,0,0]
	s_waitcnt lgkmcnt(0)
	v_mfma_scale_f32_32x32x64_f8f6f4 v[48:63], v[120:127], v[184:191], v[48:63], v237, v235 op_sel_hi:[0,0,0]
	s_mov_b32 exec_hi, 0
	ds_write_b32 v222, v194
	s_mov_b64 exec, -1
	s_waitcnt lgkmcnt(0)
	ds_read_b128 v[64:67], v223 offset:0
	ds_read_b128 v[68:71], v223 offset:32
	ds_read_b128 v[72:75], v223 offset:64
	ds_read_b128 v[76:79], v223 offset:96
	v_lshrrev_b32_e32 v231, 6, v192
	v_bfe_u32 v229, v192, 5, 1
	v_lshl_add_u32 v231, v231, 3, v229
	v_and_b32_e32 v201, 31, v192
	v_lshlrev_b32_e32 v231, 14, v231
	v_lshl_add_u32 v225, v201, 1, v231
	s_waitcnt lgkmcnt(0)
	v_rcp_f32_e32 v64, v64
	v_rcp_f32_e32 v65, v65
	v_rcp_f32_e32 v66, v66
	v_rcp_f32_e32 v67, v67
	v_rcp_f32_e32 v68, v68
	v_rcp_f32_e32 v69, v69
	v_rcp_f32_e32 v70, v70
	v_rcp_f32_e32 v71, v71
	v_rcp_f32_e32 v72, v72
	v_rcp_f32_e32 v73, v73
	v_rcp_f32_e32 v74, v74
	v_rcp_f32_e32 v75, v75
	v_rcp_f32_e32 v76, v76
	v_rcp_f32_e32 v77, v77
	v_rcp_f32_e32 v78, v78
	v_rcp_f32_e32 v79, v79
	s_nop 0
	v_mul_f32_e32 v64, 0x42000000, v64
	v_mul_f32_e32 v65, 0x42000000, v65
	v_mul_f32_e32 v66, 0x42000000, v66
	v_mul_f32_e32 v67, 0x42000000, v67
	v_mul_f32_e32 v68, 0x42000000, v68
	v_mul_f32_e32 v69, 0x42000000, v69
	v_mul_f32_e32 v70, 0x42000000, v70
	v_mul_f32_e32 v71, 0x42000000, v71
	v_mul_f32_e32 v72, 0x42000000, v72
	v_mul_f32_e32 v73, 0x42000000, v73
	v_mul_f32_e32 v74, 0x42000000, v74
	v_mul_f32_e32 v75, 0x42000000, v75
	v_mul_f32_e32 v76, 0x42000000, v76
	v_mul_f32_e32 v77, 0x42000000, v77
	v_mul_f32_e32 v78, 0x42000000, v78
	v_mul_f32_e32 v79, 0x42000000, v79
	s_nop 7
	v_mul_f32_e32 v80, v0, v64
	v_cvt_pk_bf16_f32 v80, v80, v195
	v_mul_f32_e32 v81, v16, v64
	v_cvt_pk_bf16_f32 v81, v81, v195
	v_mul_f32_e32 v82, v32, v64
	v_cvt_pk_bf16_f32 v82, v82, v195
	v_mul_f32_e32 v83, v48, v64
	v_cvt_pk_bf16_f32 v83, v83, v195
	global_store_short v225, v80, s[16:17] offset:0
	global_store_short v225, v81, s[16:17] offset:64
	global_store_short v225, v82, s[16:17] offset:128
	global_store_short v225, v83, s[16:17] offset:192
	v_add_u32_e32 v224, 0x1000, v225
	v_mul_f32_e32 v80, v1, v65
	v_cvt_pk_bf16_f32 v80, v80, v195
	v_mul_f32_e32 v81, v17, v65
	v_cvt_pk_bf16_f32 v81, v81, v195
	v_mul_f32_e32 v82, v33, v65
	v_cvt_pk_bf16_f32 v82, v82, v195
	v_mul_f32_e32 v83, v49, v65
	v_cvt_pk_bf16_f32 v83, v83, v195
	global_store_short v224, v80, s[16:17] offset:0
	global_store_short v224, v81, s[16:17] offset:64
	global_store_short v224, v82, s[16:17] offset:128
	global_store_short v224, v83, s[16:17] offset:192
	v_add_u32_e32 v224, 0x2000, v225
	v_mul_f32_e32 v80, v2, v66
	v_cvt_pk_bf16_f32 v80, v80, v195
	v_mul_f32_e32 v81, v18, v66
	v_cvt_pk_bf16_f32 v81, v81, v195
	v_mul_f32_e32 v82, v34, v66
	v_cvt_pk_bf16_f32 v82, v82, v195
	v_mul_f32_e32 v83, v50, v66
	v_cvt_pk_bf16_f32 v83, v83, v195
	global_store_short v224, v80, s[16:17] offset:0
	global_store_short v224, v81, s[16:17] offset:64
	global_store_short v224, v82, s[16:17] offset:128
	global_store_short v224, v83, s[16:17] offset:192
	v_add_u32_e32 v224, 0x3000, v225
	v_mul_f32_e32 v80, v3, v67
	v_cvt_pk_bf16_f32 v80, v80, v195
	v_mul_f32_e32 v81, v19, v67
	v_cvt_pk_bf16_f32 v81, v81, v195
	v_mul_f32_e32 v82, v35, v67
	v_cvt_pk_bf16_f32 v82, v82, v195
	v_mul_f32_e32 v83, v51, v67
	v_cvt_pk_bf16_f32 v83, v83, v195
	global_store_short v224, v80, s[16:17] offset:0
	global_store_short v224, v81, s[16:17] offset:64
	global_store_short v224, v82, s[16:17] offset:128
	global_store_short v224, v83, s[16:17] offset:192
	v_add_u32_e32 v224, 0x8000, v225
	v_mul_f32_e32 v80, v4, v68
	v_cvt_pk_bf16_f32 v80, v80, v195
	v_mul_f32_e32 v81, v20, v68
	v_cvt_pk_bf16_f32 v81, v81, v195
	v_mul_f32_e32 v82, v36, v68
	v_cvt_pk_bf16_f32 v82, v82, v195
	v_mul_f32_e32 v83, v52, v68
	v_cvt_pk_bf16_f32 v83, v83, v195
	global_store_short v224, v80, s[16:17] offset:0
	global_store_short v224, v81, s[16:17] offset:64
	global_store_short v224, v82, s[16:17] offset:128
	global_store_short v224, v83, s[16:17] offset:192
	v_add_u32_e32 v224, 0x9000, v225
	v_mul_f32_e32 v80, v5, v69
	v_cvt_pk_bf16_f32 v80, v80, v195
	v_mul_f32_e32 v81, v21, v69
	v_cvt_pk_bf16_f32 v81, v81, v195
	v_mul_f32_e32 v82, v37, v69
	v_cvt_pk_bf16_f32 v82, v82, v195
	v_mul_f32_e32 v83, v53, v69
	v_cvt_pk_bf16_f32 v83, v83, v195
	global_store_short v224, v80, s[16:17] offset:0
	global_store_short v224, v81, s[16:17] offset:64
	global_store_short v224, v82, s[16:17] offset:128
	global_store_short v224, v83, s[16:17] offset:192
	v_add_u32_e32 v224, 0xa000, v225
	v_mul_f32_e32 v80, v6, v70
	v_cvt_pk_bf16_f32 v80, v80, v195
	v_mul_f32_e32 v81, v22, v70
	v_cvt_pk_bf16_f32 v81, v81, v195
	v_mul_f32_e32 v82, v38, v70
	v_cvt_pk_bf16_f32 v82, v82, v195
	v_mul_f32_e32 v83, v54, v70
	v_cvt_pk_bf16_f32 v83, v83, v195
	global_store_short v224, v80, s[16:17] offset:0
	global_store_short v224, v81, s[16:17] offset:64
	global_store_short v224, v82, s[16:17] offset:128
; __device__ __forceinline__ bf16_t f2bf(float f) { return (bf16_t)(cvt_pk_bf16(f, 0.f) & 0xffffu); }
; __device__ __forceinline__ int crow(int r, int hi) { return (r & 3) + 8 * (r >> 2) + 4 * hi; }
; __device__ __forceinline__ void attn_body(const unsigned char* __restrict__ Qb, const unsigned char* __restrict__ Kh, const unsigned char* __restrict__ Vt,
;                                           bf16_t* __restrict__ Ob, int seq, char* lds) {
;     ...
;   for (int r = 0; r < 16; ++r) { int orow = crow(r, hi);
;     for (int d0 = 0; d0 < 4; ++d0) Ow[(long)orow * LDO + d0 * 32 + r32] = f2bf(o[d0][r] * rli[r]); }
;   asm volatile("s_waitcnt vmcnt(0)" ::: "memory");
;   __syncthreads();
; __global__ void __launch_bounds__(512) mega_fwd(Params p) {
;     ...
;             for (int it = bx; it < 256; it += G) { const int h = it & 7, qb = it >> 3;
;                 att::attn_body((const unsigned char*)B.Q + ((size_t)h * S_ + qb * 256) * 192, (const unsigned char*)B.K + (size_t)h * S_ * 192, (const unsigned char*)B.V + (size_t)h * 128 * S_,
;                                B.Y + (size_t)(qb * 256) * DM + 1024 + h * 128, S_, (char*)lds_raw); }
	global_store_short v224, v83, s[16:17] offset:192
	v_add_u32_e32 v224, 0xb000, v225
	v_mul_f32_e32 v80, v7, v71
	v_cvt_pk_bf16_f32 v80, v80, v195
	v_mul_f32_e32 v81, v23, v71
	v_cvt_pk_bf16_f32 v81, v81, v195
	v_mul_f32_e32 v82, v39, v71
	v_cvt_pk_bf16_f32 v82, v82, v195
	v_mul_f32_e32 v83, v55, v71
	v_cvt_pk_bf16_f32 v83, v83, v195
	global_store_short v224, v80, s[16:17] offset:0
	global_store_short v224, v81, s[16:17] offset:64
	global_store_short v224, v82, s[16:17] offset:128
	global_store_short v224, v83, s[16:17] offset:192
	v_add_u32_e32 v224, 0x10000, v225
	v_mul_f32_e32 v80, v8, v72
	v_cvt_pk_bf16_f32 v80, v80, v195
	v_mul_f32_e32 v81, v24, v72
	v_cvt_pk_bf16_f32 v81, v81, v195
	v_mul_f32_e32 v82, v40, v72
	v_cvt_pk_bf16_f32 v82, v82, v195
	v_mul_f32_e32 v83, v56, v72
	v_cvt_pk_bf16_f32 v83, v83, v195
	global_store_short v224, v80, s[16:17] offset:0
	global_store_short v224, v81, s[16:17] offset:64
	global_store_short v224, v82, s[16:17] offset:128
	global_store_short v224, v83, s[16:17] offset:192
	v_add_u32_e32 v224, 0x11000, v225
	v_mul_f32_e32 v80, v9, v73
	v_cvt_pk_bf16_f32 v80, v80, v195
	v_mul_f32_e32 v81, v25, v73
	v_cvt_pk_bf16_f32 v81, v81, v195
	v_mul_f32_e32 v82, v41, v73
	v_cvt_pk_bf16_f32 v82, v82, v195
	v_mul_f32_e32 v83, v57, v73
	v_cvt_pk_bf16_f32 v83, v83, v195
	global_store_short v224, v80, s[16:17] offset:0
	global_store_short v224, v81, s[16:17] offset:64
	global_store_short v224, v82, s[16:17] offset:128
	global_store_short v224, v83, s[16:17] offset:192
	v_add_u32_e32 v224, 0x12000, v225
	v_mul_f32_e32 v80, v10, v74
	v_cvt_pk_bf16_f32 v80, v80, v195
	v_mul_f32_e32 v81, v26, v74
	v_cvt_pk_bf16_f32 v81, v81, v195
	v_mul_f32_e32 v82, v42, v74
	v_cvt_pk_bf16_f32 v82, v82, v195
	v_mul_f32_e32 v83, v58, v74
	v_cvt_pk_bf16_f32 v83, v83, v195
	global_store_short v224, v80, s[16:17] offset:0
	global_store_short v224, v81, s[16:17] offset:64
	global_store_short v224, v82, s[16:17] offset:128
	global_store_short v224, v83, s[16:17] offset:192
	v_add_u32_e32 v224, 0x13000, v225
	v_mul_f32_e32 v80, v11, v75
	v_cvt_pk_bf16_f32 v80, v80, v195
	v_mul_f32_e32 v81, v27, v75
	v_cvt_pk_bf16_f32 v81, v81, v195
	v_mul_f32_e32 v82, v43, v75
	v_cvt_pk_bf16_f32 v82, v82, v195
	v_mul_f32_e32 v83, v59, v75
	v_cvt_pk_bf16_f32 v83, v83, v195
	global_store_short v224, v80, s[16:17] offset:0
	global_store_short v224, v81, s[16:17] offset:64
	global_store_short v224, v82, s[16:17] offset:128
	global_store_short v224, v83, s[16:17] offset:192
	v_add_u32_e32 v224, 0x18000, v225
	v_mul_f32_e32 v80, v12, v76
	v_cvt_pk_bf16_f32 v80, v80, v195
	v_mul_f32_e32 v81, v28, v76
	v_cvt_pk_bf16_f32 v81, v81, v195
	v_mul_f32_e32 v82, v44, v76
	v_cvt_pk_bf16_f32 v82, v82, v195
	v_mul_f32_e32 v83, v60, v76
	v_cvt_pk_bf16_f32 v83, v83, v195
	global_store_short v224, v80, s[16:17] offset:0
	global_store_short v224, v81, s[16:17] offset:64
	global_store_short v224, v82, s[16:17] offset:128
	global_store_short v224, v83, s[16:17] offset:192
	v_add_u32_e32 v224, 0x19000, v225
	v_mul_f32_e32 v80, v13, v77
	v_cvt_pk_bf16_f32 v80, v80, v195
	v_mul_f32_e32 v81, v29, v77
	v_cvt_pk_bf16_f32 v81, v81, v195
	v_mul_f32_e32 v82, v45, v77
	v_cvt_pk_bf16_f32 v82, v82, v195
	v_mul_f32_e32 v83, v61, v77
	v_cvt_pk_bf16_f32 v83, v83, v195
	global_store_short v224, v80, s[16:17] offset:0
	global_store_short v224, v81, s[16:17] offset:64
	global_store_short v224, v82, s[16:17] offset:128
	global_store_short v224, v83, s[16:17] offset:192
	v_add_u32_e32 v224, 0x1a000, v225
	v_mul_f32_e32 v80, v14, v78
	v_cvt_pk_bf16_f32 v80, v80, v195
	v_mul_f32_e32 v81, v30, v78
	v_cvt_pk_bf16_f32 v81, v81, v195
	v_mul_f32_e32 v82, v46, v78
	v_cvt_pk_bf16_f32 v82, v82, v195
	v_mul_f32_e32 v83, v62, v78
	v_cvt_pk_bf16_f32 v83, v83, v195
	global_store_short v224, v80, s[16:17] offset:0
	global_store_short v224, v81, s[16:17] offset:64
	global_store_short v224, v82, s[16:17] offset:128
	global_store_short v224, v83, s[16:17] offset:192
	v_add_u32_e32 v224, 0x1b000, v225
	v_mul_f32_e32 v80, v15, v79
	v_cvt_pk_bf16_f32 v80, v80, v195
	v_mul_f32_e32 v81, v31, v79
	v_cvt_pk_bf16_f32 v81, v81, v195
	v_mul_f32_e32 v82, v47, v79
	v_cvt_pk_bf16_f32 v82, v82, v195
	v_mul_f32_e32 v83, v63, v79
	v_cvt_pk_bf16_f32 v83, v83, v195
	global_store_short v224, v80, s[16:17] offset:0
	global_store_short v224, v81, s[16:17] offset:64
	global_store_short v224, v82, s[16:17] offset:128
	global_store_short v224, v83, s[16:17] offset:192
	s_waitcnt vmcnt(0)
	v_readlane_b32 s0, v252, 9
	s_nop 1
	s_add_i32 s25, s25, s0
	s_add_i32 s24, s24, s0
	s_cmpk_gt_i32 s25, 0xff
	s_waitcnt lgkmcnt(0)
	s_barrier
	v_readlane_b32 s1, v252, 10
	s_cbranch_scc1 .LBB0_297
	s_branch .LBB0_260
; __device__ __forceinline__ void partialSM(f32x16& p0, f32x16& p1, float& m_reg, float& mn, float& alpha) {
;     ...
;   { auto rr = __builtin_amdgcn_permlane32_swap(__float_as_uint(pmax), __float_as_uint(pmax), false, false);
;     pmax = fmaxf(__uint_as_float(rr[0]), __uint_as_float(rr[1])); }
;   if (__builtin_expect(__all(pmax - m_reg <= THR / SCALE), 1)) { mn = m_reg; alpha = 1.f; }
;   else { mn = fmaxf(m_reg, pmax); alpha = __builtin_amdgcn_exp2f((m_reg - mn) * C); m_reg = mn; }
.Latt_rare:
	v_sub_f32_e32 v229, v228, v227
	v_max_f32_e32 v229, v193, v229
	v_sub_f32_e32 v231, v193, v229
	v_exp_f32_e32 v226, v231
	v_mov_b32_e32 v193, v229
	v_sub_f32_e32 v231, v236, v229
	v_sub_f32_e32 v229, v231, v227
	v_mov_b32_e32 v227, v231
	v_add_f32_e32 v64, v64, v229
	v_add_f32_e32 v65, v65, v229
	v_add_f32_e32 v66, v66, v229
	v_add_f32_e32 v67, v67, v229
	v_add_f32_e32 v68, v68, v229
	v_add_f32_e32 v69, v69, v229
	v_add_f32_e32 v70, v70, v229
	v_add_f32_e32 v71, v71, v229
	v_add_f32_e32 v72, v72, v229
	v_add_f32_e32 v73, v73, v229
	v_add_f32_e32 v74, v74, v229
	v_add_f32_e32 v75, v75, v229
	v_add_f32_e32 v76, v76, v229
	v_add_f32_e32 v77, v77, v229
	v_add_f32_e32 v78, v78, v229
	v_add_f32_e32 v79, v79, v229
	v_add_f32_e32 v80, v80, v229
	v_add_f32_e32 v81, v81, v229
	v_add_f32_e32 v82, v82, v229
	v_add_f32_e32 v83, v83, v229
	v_add_f32_e32 v84, v84, v229
	v_add_f32_e32 v85, v85, v229
	v_add_f32_e32 v86, v86, v229
	v_add_f32_e32 v87, v87, v229
	v_add_f32_e32 v88, v88, v229
	v_add_f32_e32 v89, v89, v229
	v_add_f32_e32 v90, v90, v229
	v_add_f32_e32 v91, v91, v229
	v_add_f32_e32 v92, v92, v229
	v_add_f32_e32 v93, v93, v229
	v_add_f32_e32 v94, v94, v229
	v_add_f32_e32 v95, v95, v229
	v_mov_b32_e32 v160, v227
	v_mov_b32_e32 v161, v227
	v_mov_b32_e32 v162, v227
	v_mov_b32_e32 v163, v227
	v_mov_b32_e32 v164, v227
	v_mov_b32_e32 v165, v227
	v_mov_b32_e32 v166, v227
	v_mov_b32_e32 v167, v227
	v_mov_b32_e32 v168, v227
	v_mov_b32_e32 v169, v227
	v_mov_b32_e32 v170, v227
	v_mov_b32_e32 v171, v227
	v_mov_b32_e32 v172, v227
	v_mov_b32_e32 v173, v227
	v_mov_b32_e32 v174, v227
	v_mov_b32_e32 v175, v227
	s_mov_b32 exec_hi, 0
	ds_write_b32 v222, v226 offset:128
	s_mov_b64 exec, -1
	s_waitcnt lgkmcnt(0)
	ds_read_b128 v[176:179], v223 offset:128
	ds_read_b128 v[180:183], v223 offset:160
	ds_read_b128 v[184:187], v223 offset:192
	ds_read_b128 v[188:191], v223 offset:224
	s_waitcnt lgkmcnt(0)
	v_mul_f32_e32 v0, v0, v176
	v_mul_f32_e32 v1, v1, v177
	v_mul_f32_e32 v2, v2, v178
	v_mul_f32_e32 v3, v3, v179
	v_mul_f32_e32 v4, v4, v180
	v_mul_f32_e32 v5, v5, v181
	v_mul_f32_e32 v6, v6, v182
	v_mul_f32_e32 v7, v7, v183
	v_mul_f32_e32 v8, v8, v184
	v_mul_f32_e32 v9, v9, v185
	v_mul_f32_e32 v10, v10, v186
	v_mul_f32_e32 v11, v11, v187
	v_mul_f32_e32 v12, v12, v188
	v_mul_f32_e32 v13, v13, v189
	v_mul_f32_e32 v14, v14, v190
	v_mul_f32_e32 v15, v15, v191
	v_mul_f32_e32 v16, v16, v176
	v_mul_f32_e32 v17, v17, v177
	v_mul_f32_e32 v18, v18, v178
	v_mul_f32_e32 v19, v19, v179
	v_mul_f32_e32 v20, v20, v180
	v_mul_f32_e32 v21, v21, v181
	v_mul_f32_e32 v22, v22, v182
	v_mul_f32_e32 v23, v23, v183
	v_mul_f32_e32 v24, v24, v184
	v_mul_f32_e32 v25, v25, v185
	v_mul_f32_e32 v26, v26, v186
	v_mul_f32_e32 v27, v27, v187
	v_mul_f32_e32 v28, v28, v188
	v_mul_f32_e32 v29, v29, v189
	v_mul_f32_e32 v30, v30, v190
	v_mul_f32_e32 v31, v31, v191
	v_mul_f32_e32 v32, v32, v176
	v_mul_f32_e32 v33, v33, v177
	v_mul_f32_e32 v34, v34, v178
	v_mul_f32_e32 v35, v35, v179
	v_mul_f32_e32 v36, v36, v180
	v_mul_f32_e32 v37, v37, v181
	v_mul_f32_e32 v38, v38, v182
	v_mul_f32_e32 v39, v39, v183
	v_mul_f32_e32 v40, v40, v184
	v_mul_f32_e32 v41, v41, v185
	v_mul_f32_e32 v42, v42, v186
	v_mul_f32_e32 v43, v43, v187
	v_mul_f32_e32 v44, v44, v188
	v_mul_f32_e32 v45, v45, v189
	v_mul_f32_e32 v46, v46, v190
	v_mul_f32_e32 v47, v47, v191
	v_mul_f32_e32 v48, v48, v176
	v_mul_f32_e32 v49, v49, v177
	v_mul_f32_e32 v50, v50, v178
	v_mul_f32_e32 v51, v51, v179
	v_mul_f32_e32 v52, v52, v180
	v_mul_f32_e32 v53, v53, v181
	v_mul_f32_e32 v54, v54, v182
	v_mul_f32_e32 v55, v55, v183
	v_mul_f32_e32 v56, v56, v184
	v_mul_f32_e32 v57, v57, v185
	v_mul_f32_e32 v58, v58, v186
	v_mul_f32_e32 v59, v59, v187
	v_mul_f32_e32 v60, v60, v188
	v_mul_f32_e32 v61, v61, v189
	v_mul_f32_e32 v62, v62, v190
	v_mul_f32_e32 v63, v63, v191
	s_cmp_eq_u32 s5, 0
	s_cbranch_scc1 .Latt_rare_back_0
	s_cmp_eq_u32 s5, 1
	s_cbranch_scc1 .Latt_rare_back_1
	s_cmp_eq_u32 s5, 2
	s_cbranch_scc1 .Latt_rare_back_2
	s_branch .Latt_rare_back_3
